# v36 plus nt cache policy on the read-once G loads of the ple GEMM epilogue
# baseline (speedup 1.0000x reference)
; DI float bflo(unsigned w) { return __uint_as_float(w << 16); }
; DI float bfhi(unsigned w) { return __uint_as_float(w & 0xffff0000u); }
; template <class F> DI void epi_iter(const f32x4 (&acc)[2][2][4][2], const Unit& u, int wr, int wc, int fr, int fq, F f) {
;     const int row0 = u.pm * 256 + wr * 64 + fr, col0 = u.pn * 256 + wc * 32 + 8 * fq;
; #pragma unroll
;     for (int ai = 0; ai < 2; ++ai)
; #pragma unroll
;         for (int m = 0; m < 4; ++m)
; #pragma unroll
;             for (int bj = 0; bj < 2; ++bj) { f(row0 + ai * 128 + m * 16, col0 + bj * 128, acc[ai][bj][m][0], acc[ai][bj][m][1]); if ((m == 3) && bj) asm volatile("" ::: "memory"); }
;     DI void operator()(const f32x4 (&acc)[2][2][4][2], const Unit& u, int wr, int wc, int fr, int fq) const {
;         float* x = X; const bf16_t* g = G;
;         epi_iter(acc, u, wr, wc, fr, fq, [&](int row, int col, f32x4 v0, f32x4 v1) {
;             const size_t o = (size_t)row * DM + col;
;             f32x4 a = *(const f32x4*)(x + o), b = *(const f32x4*)(x + o + 4);
;             const u32x4 gw = *(const u32x4*)(g + o);
;             a[0] += v0[0] * bflo(gw.x); a[1] += v0[1] * bfhi(gw.x); a[2] += v0[2] * bflo(gw.y); a[3] += v0[3] * bfhi(gw.y);
;             b[0] += v1[0] * bflo(gw.z); b[1] += v1[1] * bfhi(gw.z); b[2] += v1[2] * bflo(gw.w); b[3] += v1[3] * bfhi(gw.w);
;             *(f32x4*)(x + o) = a; *(f32x4*)(x + o + 4) = b;
.LBB0_937:
	v_lshl_add_u32 v144, s65, 8, v146
	v_lshl_or_b32 v140, s64, 8, v153
	v_ashrrev_i32_e32 v145, 31, v144
	v_lshlrev_b64 v[142:143], 10, v[144:145]
	v_ashrrev_i32_e32 v141, 31, v140
	v_lshl_add_u64 v[164:165], v[142:143], 0, v[140:141]
	v_lshl_add_u64 v[168:169], v[164:165], 2, s[88:89]
	v_lshl_add_u64 v[164:165], v[164:165], 1, s[24:25]
	global_load_dwordx4 v[156:159], v[168:169], off offset:16
	global_load_dwordx4 v[160:163], v[168:169], off
	s_mov_b64 s[2:3], 0x20000
	global_load_dwordx4 v[164:167], v[164:165], off nt
	s_and_b64 vcc, exec, s[38:39]
	s_waitcnt vmcnt(0)
	v_lshlrev_b32_e32 v170, 16, v164
	v_and_b32_e32 v171, 0xffff0000, v164
	v_pk_fma_f32 v[126:127], v[126:127], v[170:171], v[160:161]
	v_lshlrev_b32_e32 v160, 16, v165
	v_and_b32_e32 v161, 0xffff0000, v165
	v_pk_fma_f32 v[128:129], v[128:129], v[160:161], v[162:163]
	v_lshlrev_b32_e32 v160, 16, v166
	v_and_b32_e32 v161, 0xffff0000, v166
	v_pk_fma_f32 v[122:123], v[122:123], v[160:161], v[156:157]
	v_lshlrev_b32_e32 v156, 16, v167
	v_and_b32_e32 v157, 0xffff0000, v167
	v_pk_fma_f32 v[124:125], v[124:125], v[156:157], v[158:159]
	global_store_dwordx4 v[168:169], v[126:129], off
	global_store_dwordx4 v[168:169], v[122:125], off offset:16
	global_load_dwordx4 v[124:127], v[168:169], off offset:528
	s_nop 0
	global_load_dwordx4 v[156:159], v[168:169], off offset:512
	v_or_b32_e32 v122, 0x80, v140
	v_ashrrev_i32_e32 v123, 31, v122
	v_lshl_add_u64 v[128:129], v[142:143], 0, v[122:123]
	v_lshl_add_u64 v[128:129], v[128:129], 1, s[24:25]
	global_load_dwordx4 v[160:163], v[128:129], off nt
	s_waitcnt vmcnt(0)
	v_lshlrev_b32_e32 v128, 16, v160
	v_and_b32_e32 v129, 0xffff0000, v160
	v_pk_fma_f32 v[118:119], v[118:119], v[128:129], v[156:157]
	v_lshlrev_b32_e32 v128, 16, v161
	v_and_b32_e32 v129, 0xffff0000, v161
	v_pk_fma_f32 v[120:121], v[120:121], v[128:129], v[158:159]
	v_lshlrev_b32_e32 v128, 16, v162
	v_and_b32_e32 v129, 0xffff0000, v162
	v_pk_fma_f32 v[114:115], v[114:115], v[128:129], v[124:125]
	v_lshlrev_b32_e32 v124, 16, v163
	v_and_b32_e32 v125, 0xffff0000, v163
	v_pk_fma_f32 v[116:117], v[116:117], v[124:125], v[126:127]
	global_store_dwordx4 v[168:169], v[118:121], off offset:512
	global_store_dwordx4 v[168:169], v[114:117], off offset:528
	s_nop 1
	v_or_b32_e32 v114, 16, v144
	v_ashrrev_i32_e32 v115, 31, v114
	v_lshlrev_b64 v[120:121], 10, v[114:115]
	v_lshl_add_u64 v[128:129], v[120:121], 0, v[140:141]
	v_lshl_add_u64 v[114:115], v[128:129], 2, s[88:89]
	v_lshl_add_u64 v[128:129], v[128:129], 1, s[24:25]
	global_load_dwordx4 v[116:119], v[114:115], off offset:16
	global_load_dwordx4 v[124:127], v[114:115], off
	global_load_dwordx4 v[156:159], v[128:129], off nt
	s_waitcnt vmcnt(0)
	v_lshlrev_b32_e32 v128, 16, v156
	v_and_b32_e32 v129, 0xffff0000, v156
	v_pk_fma_f32 v[110:111], v[110:111], v[128:129], v[124:125]
	v_lshlrev_b32_e32 v124, 16, v157
	v_and_b32_e32 v125, 0xffff0000, v157
	v_pk_fma_f32 v[112:113], v[112:113], v[124:125], v[126:127]
	v_lshlrev_b32_e32 v124, 16, v158
	v_and_b32_e32 v125, 0xffff0000, v158
	v_pk_fma_f32 v[106:107], v[106:107], v[124:125], v[116:117]
	v_lshlrev_b32_e32 v116, 16, v159
	v_and_b32_e32 v117, 0xffff0000, v159
	v_pk_fma_f32 v[108:109], v[108:109], v[116:117], v[118:119]
	v_lshl_add_u64 v[116:117], v[120:121], 0, v[122:123]
	global_store_dwordx4 v[114:115], v[110:113], off
	global_store_dwordx4 v[114:115], v[106:109], off offset:16
	v_lshl_add_u64 v[116:117], v[116:117], 1, s[24:25]
	global_load_dwordx4 v[106:109], v[114:115], off offset:528
	global_load_dwordx4 v[110:113], v[114:115], off offset:512
	s_nop 0
	global_load_dwordx4 v[116:119], v[116:117], off nt
	s_waitcnt vmcnt(0)
	v_lshlrev_b32_e32 v120, 16, v116
	v_and_b32_e32 v121, 0xffff0000, v116
	v_pk_fma_f32 v[102:103], v[102:103], v[120:121], v[110:111]
	v_lshlrev_b32_e32 v110, 16, v117
	v_and_b32_e32 v111, 0xffff0000, v117
	v_pk_fma_f32 v[104:105], v[104:105], v[110:111], v[112:113]
	v_lshlrev_b32_e32 v110, 16, v118
	v_and_b32_e32 v111, 0xffff0000, v118
	v_pk_fma_f32 v[98:99], v[98:99], v[110:111], v[106:107]
	v_lshlrev_b32_e32 v106, 16, v119
	v_and_b32_e32 v107, 0xffff0000, v119
	v_pk_fma_f32 v[100:101], v[100:101], v[106:107], v[108:109]
	global_store_dwordx4 v[114:115], v[102:105], off offset:512
	global_store_dwordx4 v[114:115], v[98:101], off offset:528
	s_nop 1
	v_or_b32_e32 v98, 32, v144
	v_ashrrev_i32_e32 v99, 31, v98
	v_lshlrev_b64 v[112:113], 10, v[98:99]
	v_lshl_add_u64 v[108:109], v[112:113], 0, v[140:141]
	v_lshl_add_u64 v[98:99], v[108:109], 2, s[88:89]
	v_lshl_add_u64 v[108:109], v[108:109], 1, s[24:25]
	global_load_dwordx4 v[100:103], v[98:99], off offset:16
	global_load_dwordx4 v[104:107], v[98:99], off
	s_nop 0
	global_load_dwordx4 v[108:111], v[108:109], off nt
	s_waitcnt vmcnt(0)
	v_lshlrev_b32_e32 v114, 16, v108
	v_and_b32_e32 v115, 0xffff0000, v108
	v_pk_fma_f32 v[94:95], v[94:95], v[114:115], v[104:105]
	v_lshlrev_b32_e32 v104, 16, v109
	v_and_b32_e32 v105, 0xffff0000, v109
	v_pk_fma_f32 v[96:97], v[96:97], v[104:105], v[106:107]
	v_lshlrev_b32_e32 v104, 16, v110
	v_and_b32_e32 v105, 0xffff0000, v110
	v_pk_fma_f32 v[90:91], v[90:91], v[104:105], v[100:101]
	v_lshlrev_b32_e32 v100, 16, v111
	v_and_b32_e32 v101, 0xffff0000, v111
	v_pk_fma_f32 v[92:93], v[92:93], v[100:101], v[102:103]
	v_lshl_add_u64 v[100:101], v[112:113], 0, v[122:123]
	global_store_dwordx4 v[98:99], v[94:97], off
	global_store_dwordx4 v[98:99], v[90:93], off offset:16
	v_lshl_add_u64 v[100:101], v[100:101], 1, s[24:25]
	global_load_dwordx4 v[90:93], v[98:99], off offset:528
	global_load_dwordx4 v[94:97], v[98:99], off offset:512
	s_nop 0
	global_load_dwordx4 v[100:103], v[100:101], off nt
	s_waitcnt vmcnt(0)
; DI float bflo(unsigned w) { return __uint_as_float(w << 16); }
; DI float bfhi(unsigned w) { return __uint_as_float(w & 0xffff0000u); }
; template <class F> DI void epi_iter(const f32x4 (&acc)[2][2][4][2], const Unit& u, int wr, int wc, int fr, int fq, F f) {
;     const int row0 = u.pm * 256 + wr * 64 + fr, col0 = u.pn * 256 + wc * 32 + 8 * fq;
; #pragma unroll
;     for (int ai = 0; ai < 2; ++ai)
; #pragma unroll
;         for (int m = 0; m < 4; ++m)
; #pragma unroll
;             for (int bj = 0; bj < 2; ++bj) { f(row0 + ai * 128 + m * 16, col0 + bj * 128, acc[ai][bj][m][0], acc[ai][bj][m][1]); if ((m == 3) && bj) asm volatile("" ::: "memory"); }
;     DI void operator()(const f32x4 (&acc)[2][2][4][2], const Unit& u, int wr, int wc, int fr, int fq) const {
;     ...
;         epi_iter(acc, u, wr, wc, fr, fq, [&](int row, int col, f32x4 v0, f32x4 v1) {
;             const size_t o = (size_t)row * DM + col;
;             f32x4 a = *(const f32x4*)(x + o), b = *(const f32x4*)(x + o + 4);
;             const u32x4 gw = *(const u32x4*)(g + o);
;             a[0] += v0[0] * bflo(gw.x); a[1] += v0[1] * bfhi(gw.x); a[2] += v0[2] * bflo(gw.y); a[3] += v0[3] * bfhi(gw.y);
;             b[0] += v1[0] * bflo(gw.z); b[1] += v1[1] * bfhi(gw.z); b[2] += v1[2] * bflo(gw.w); b[3] += v1[3] * bfhi(gw.w);
;             *(f32x4*)(x + o) = a; *(f32x4*)(x + o + 4) = b;
	v_lshlrev_b32_e32 v104, 16, v100
	v_and_b32_e32 v105, 0xffff0000, v100
	v_pk_fma_f32 v[86:87], v[86:87], v[104:105], v[94:95]
	v_lshlrev_b32_e32 v94, 16, v101
	v_and_b32_e32 v95, 0xffff0000, v101
	v_pk_fma_f32 v[88:89], v[88:89], v[94:95], v[96:97]
	v_lshlrev_b32_e32 v94, 16, v102
	v_and_b32_e32 v95, 0xffff0000, v102
	v_pk_fma_f32 v[82:83], v[82:83], v[94:95], v[90:91]
	v_lshlrev_b32_e32 v90, 16, v103
	v_and_b32_e32 v91, 0xffff0000, v103
	v_pk_fma_f32 v[84:85], v[84:85], v[90:91], v[92:93]
	global_store_dwordx4 v[98:99], v[86:89], off offset:512
	global_store_dwordx4 v[98:99], v[82:85], off offset:528
	s_nop 1
	v_or_b32_e32 v82, 48, v144
	v_ashrrev_i32_e32 v83, 31, v82
	v_lshlrev_b64 v[96:97], 10, v[82:83]
	v_lshl_add_u64 v[92:93], v[96:97], 0, v[140:141]
	v_lshl_add_u64 v[82:83], v[92:93], 2, s[88:89]
	v_lshl_add_u64 v[92:93], v[92:93], 1, s[24:25]
	global_load_dwordx4 v[84:87], v[82:83], off offset:16
	global_load_dwordx4 v[88:91], v[82:83], off
	s_nop 0
	global_load_dwordx4 v[92:95], v[92:93], off nt
	s_waitcnt vmcnt(0)
	v_lshlrev_b32_e32 v98, 16, v92
	v_and_b32_e32 v99, 0xffff0000, v92
	v_pk_fma_f32 v[78:79], v[78:79], v[98:99], v[88:89]
	v_lshlrev_b32_e32 v88, 16, v93
	v_and_b32_e32 v89, 0xffff0000, v93
	v_pk_fma_f32 v[80:81], v[80:81], v[88:89], v[90:91]
	v_lshlrev_b32_e32 v88, 16, v94
	v_and_b32_e32 v89, 0xffff0000, v94
	v_pk_fma_f32 v[74:75], v[74:75], v[88:89], v[84:85]
	v_lshlrev_b32_e32 v84, 16, v95
	v_and_b32_e32 v85, 0xffff0000, v95
	v_pk_fma_f32 v[76:77], v[76:77], v[84:85], v[86:87]
	v_lshl_add_u64 v[84:85], v[96:97], 0, v[122:123]
	global_store_dwordx4 v[82:83], v[78:81], off
	global_store_dwordx4 v[82:83], v[74:77], off offset:16
	v_lshl_add_u64 v[84:85], v[84:85], 1, s[24:25]
	global_load_dwordx4 v[74:77], v[82:83], off offset:528
	global_load_dwordx4 v[78:81], v[82:83], off offset:512
	s_nop 0
	global_load_dwordx4 v[84:87], v[84:85], off nt
	s_waitcnt vmcnt(0)
	v_lshlrev_b32_e32 v88, 16, v84
	v_and_b32_e32 v89, 0xffff0000, v84
	v_pk_fma_f32 v[70:71], v[70:71], v[88:89], v[78:79]
	v_lshlrev_b32_e32 v78, 16, v85
	v_and_b32_e32 v79, 0xffff0000, v85
	v_pk_fma_f32 v[72:73], v[72:73], v[78:79], v[80:81]
	v_lshlrev_b32_e32 v78, 16, v86
	v_and_b32_e32 v79, 0xffff0000, v86
	v_pk_fma_f32 v[66:67], v[66:67], v[78:79], v[74:75]
	v_lshlrev_b32_e32 v74, 16, v87
	v_and_b32_e32 v75, 0xffff0000, v87
	v_lshl_add_u64 v[80:81], v[142:143], 0, s[2:3]
	v_pk_fma_f32 v[68:69], v[68:69], v[74:75], v[76:77]
	global_store_dwordx4 v[82:83], v[70:73], off offset:512
	global_store_dwordx4 v[82:83], v[66:69], off offset:528
	v_lshl_add_u64 v[76:77], v[80:81], 0, v[140:141]
	s_mov_b64 s[2:3], 0x24000
	v_lshl_add_u64 v[66:67], v[76:77], 2, s[88:89]
	v_lshl_add_u64 v[76:77], v[76:77], 1, s[24:25]
	global_load_dwordx4 v[68:71], v[66:67], off offset:16
	global_load_dwordx4 v[72:75], v[66:67], off
	s_nop 0
	global_load_dwordx4 v[76:79], v[76:77], off nt
	s_waitcnt vmcnt(0)
	v_lshlrev_b32_e32 v82, 16, v76
	v_and_b32_e32 v83, 0xffff0000, v76
	v_pk_fma_f32 v[62:63], v[62:63], v[82:83], v[72:73]
	v_lshlrev_b32_e32 v72, 16, v77
	v_and_b32_e32 v73, 0xffff0000, v77
	v_pk_fma_f32 v[64:65], v[64:65], v[72:73], v[74:75]
	v_lshlrev_b32_e32 v72, 16, v78
	v_and_b32_e32 v73, 0xffff0000, v78
	v_pk_fma_f32 v[58:59], v[58:59], v[72:73], v[68:69]
	v_lshlrev_b32_e32 v68, 16, v79
	v_and_b32_e32 v69, 0xffff0000, v79
	v_pk_fma_f32 v[60:61], v[60:61], v[68:69], v[70:71]
	v_lshl_add_u64 v[68:69], v[80:81], 0, v[122:123]
	global_store_dwordx4 v[66:67], v[62:65], off
	global_store_dwordx4 v[66:67], v[58:61], off offset:16
	v_lshl_add_u64 v[68:69], v[68:69], 1, s[24:25]
	global_load_dwordx4 v[58:61], v[66:67], off offset:528
	global_load_dwordx4 v[62:65], v[66:67], off offset:512
	s_nop 0
	global_load_dwordx4 v[68:71], v[68:69], off nt
	s_waitcnt vmcnt(0)
	v_lshlrev_b32_e32 v72, 16, v68
	v_and_b32_e32 v73, 0xffff0000, v68
	v_pk_fma_f32 v[54:55], v[54:55], v[72:73], v[62:63]
	v_lshlrev_b32_e32 v62, 16, v69
	v_and_b32_e32 v63, 0xffff0000, v69
	v_pk_fma_f32 v[56:57], v[56:57], v[62:63], v[64:65]
	v_lshlrev_b32_e32 v62, 16, v70
	v_and_b32_e32 v63, 0xffff0000, v70
	v_pk_fma_f32 v[50:51], v[50:51], v[62:63], v[58:59]
	v_lshlrev_b32_e32 v58, 16, v71
	v_and_b32_e32 v59, 0xffff0000, v71
	v_lshl_add_u64 v[64:65], v[142:143], 0, s[2:3]
	v_pk_fma_f32 v[52:53], v[52:53], v[58:59], v[60:61]
	v_lshl_add_u64 v[60:61], v[64:65], 0, v[140:141]
	global_store_dwordx4 v[66:67], v[54:57], off offset:512
	global_store_dwordx4 v[66:67], v[50:53], off offset:528
	s_mov_b64 s[2:3], 0x28000
	s_nop 0
	v_lshl_add_u64 v[50:51], v[60:61], 2, s[88:89]
	v_lshl_add_u64 v[60:61], v[60:61], 1, s[24:25]
	global_load_dwordx4 v[52:55], v[50:51], off offset:16
	global_load_dwordx4 v[56:59], v[50:51], off
	s_nop 0
	global_load_dwordx4 v[60:63], v[60:61], off nt
	s_waitcnt vmcnt(0)
; #define PG8_BAR __builtin_amdgcn_s_barrier()
; DI float bflo(unsigned w) { return __uint_as_float(w << 16); }
; DI float bfhi(unsigned w) { return __uint_as_float(w & 0xffff0000u); }
; template <class Epi, class Sched, bool ALIGN_EPI = false, bool SP2 = false>
; __device__ __forceinline__ void gemm_phase(PG8_LAS unsigned char* lds, const Gemm g, const Sched& S, const Epi& E) {
;     ...
;         if constexpr (ALIGN_EPI) { if (wr == 0) PG8_BAR; }
;         if constexpr (!Epi::AFTER_DRAIN) { E(acc, cur, wr, wc, fr, fq); S.done(cur); }
;         if (!has_next) break;
; #pragma unroll
;         for (int a = 0; a < 2; ++a)
; #pragma unroll
;             for (int b = 0; b < 2; ++b)
; #pragma unroll
;                 for (int m = 0; m < 4; ++m)
; #pragma unroll
;                     for (int n = 0; n < 2; ++n) acc[a][b][m][n] = (f32x4){0.f, 0.f, 0.f, 0.f};
;         cur = nxt; cA = nA; cB = nB; ++ui;
;         if constexpr (ALIGN_EPI) { if (wr == 1) PG8_BAR; }
;     DI void operator()(const f32x4 (&acc)[2][2][4][2], const Unit& u, int wr, int wc, int fr, int fq) const {
;     ...
;         epi_iter(acc, u, wr, wc, fr, fq, [&](int row, int col, f32x4 v0, f32x4 v1) {
;             const size_t o = (size_t)row * DM + col;
;             f32x4 a = *(const f32x4*)(x + o), b = *(const f32x4*)(x + o + 4);
;             const u32x4 gw = *(const u32x4*)(g + o);
;             a[0] += v0[0] * bflo(gw.x); a[1] += v0[1] * bfhi(gw.x); a[2] += v0[2] * bflo(gw.y); a[3] += v0[3] * bfhi(gw.y);
;             b[0] += v1[0] * bflo(gw.z); b[1] += v1[1] * bfhi(gw.z); b[2] += v1[2] * bflo(gw.w); b[3] += v1[3] * bfhi(gw.w);
;             *(f32x4*)(x + o) = a; *(f32x4*)(x + o + 4) = b;
	v_lshlrev_b32_e32 v66, 16, v60
	v_and_b32_e32 v67, 0xffff0000, v60
	v_pk_fma_f32 v[46:47], v[46:47], v[66:67], v[56:57]
	v_lshlrev_b32_e32 v56, 16, v61
	v_and_b32_e32 v57, 0xffff0000, v61
	v_pk_fma_f32 v[48:49], v[48:49], v[56:57], v[58:59]
	v_lshlrev_b32_e32 v56, 16, v62
	v_and_b32_e32 v57, 0xffff0000, v62
	v_pk_fma_f32 v[42:43], v[42:43], v[56:57], v[52:53]
	v_lshlrev_b32_e32 v52, 16, v63
	v_and_b32_e32 v53, 0xffff0000, v63
	v_pk_fma_f32 v[44:45], v[44:45], v[52:53], v[54:55]
	v_lshl_add_u64 v[52:53], v[64:65], 0, v[122:123]
	global_store_dwordx4 v[50:51], v[46:49], off
	global_store_dwordx4 v[50:51], v[42:45], off offset:16
	v_lshl_add_u64 v[52:53], v[52:53], 1, s[24:25]
	global_load_dwordx4 v[42:45], v[50:51], off offset:528
	global_load_dwordx4 v[46:49], v[50:51], off offset:512
	s_nop 0
	global_load_dwordx4 v[52:55], v[52:53], off nt
	s_waitcnt vmcnt(0)
	v_lshlrev_b32_e32 v56, 16, v52
	v_and_b32_e32 v57, 0xffff0000, v52
	v_pk_fma_f32 v[38:39], v[38:39], v[56:57], v[46:47]
	v_lshlrev_b32_e32 v46, 16, v53
	v_and_b32_e32 v47, 0xffff0000, v53
	v_pk_fma_f32 v[40:41], v[40:41], v[46:47], v[48:49]
	v_lshlrev_b32_e32 v46, 16, v54
	v_and_b32_e32 v47, 0xffff0000, v54
	v_pk_fma_f32 v[34:35], v[34:35], v[46:47], v[42:43]
	v_lshlrev_b32_e32 v42, 16, v55
	v_and_b32_e32 v43, 0xffff0000, v55
	v_lshl_add_u64 v[48:49], v[142:143], 0, s[2:3]
	v_pk_fma_f32 v[36:37], v[36:37], v[42:43], v[44:45]
	v_lshl_add_u64 v[44:45], v[48:49], 0, v[140:141]
	global_store_dwordx4 v[50:51], v[38:41], off offset:512
	global_store_dwordx4 v[50:51], v[34:37], off offset:528
	s_mov_b64 s[2:3], 0x2c000
	s_nop 0
	v_lshl_add_u64 v[34:35], v[44:45], 2, s[88:89]
	v_lshl_add_u64 v[44:45], v[44:45], 1, s[24:25]
	global_load_dwordx4 v[36:39], v[34:35], off offset:16
	global_load_dwordx4 v[40:43], v[34:35], off
	s_nop 0
	global_load_dwordx4 v[44:47], v[44:45], off nt
	s_waitcnt vmcnt(0)
	v_lshlrev_b32_e32 v50, 16, v44
	v_and_b32_e32 v51, 0xffff0000, v44
	v_pk_fma_f32 v[30:31], v[30:31], v[50:51], v[40:41]
	v_lshlrev_b32_e32 v40, 16, v45
	v_and_b32_e32 v41, 0xffff0000, v45
	v_pk_fma_f32 v[32:33], v[32:33], v[40:41], v[42:43]
	v_lshlrev_b32_e32 v40, 16, v46
	v_and_b32_e32 v41, 0xffff0000, v46
	v_pk_fma_f32 v[26:27], v[26:27], v[40:41], v[36:37]
	v_lshlrev_b32_e32 v36, 16, v47
	v_and_b32_e32 v37, 0xffff0000, v47
	v_pk_fma_f32 v[28:29], v[28:29], v[36:37], v[38:39]
	v_lshl_add_u64 v[36:37], v[48:49], 0, v[122:123]
	global_store_dwordx4 v[34:35], v[30:33], off
	global_store_dwordx4 v[34:35], v[26:29], off offset:16
	v_lshl_add_u64 v[36:37], v[36:37], 1, s[24:25]
	global_load_dwordx4 v[26:29], v[34:35], off offset:528
	global_load_dwordx4 v[30:33], v[34:35], off offset:512
	s_nop 0
	global_load_dwordx4 v[36:39], v[36:37], off nt
	s_waitcnt vmcnt(0)
	v_lshlrev_b32_e32 v40, 16, v36
	v_and_b32_e32 v41, 0xffff0000, v36
	v_pk_fma_f32 v[22:23], v[22:23], v[40:41], v[30:31]
	v_lshlrev_b32_e32 v30, 16, v37
	v_and_b32_e32 v31, 0xffff0000, v37
	v_pk_fma_f32 v[24:25], v[24:25], v[30:31], v[32:33]
	v_lshlrev_b32_e32 v30, 16, v38
	v_and_b32_e32 v31, 0xffff0000, v38
	v_pk_fma_f32 v[18:19], v[18:19], v[30:31], v[26:27]
	v_lshlrev_b32_e32 v26, 16, v39
	v_and_b32_e32 v27, 0xffff0000, v39
	v_lshl_add_u64 v[32:33], v[142:143], 0, s[2:3]
	v_pk_fma_f32 v[20:21], v[20:21], v[26:27], v[28:29]
	v_lshl_add_u64 v[28:29], v[32:33], 0, v[140:141]
	global_store_dwordx4 v[34:35], v[22:25], off offset:512
	global_store_dwordx4 v[34:35], v[18:21], off offset:528
	s_mov_b64 s[2:3], -1
	s_nop 0
	v_lshl_add_u64 v[18:19], v[28:29], 2, s[88:89]
	v_lshl_add_u64 v[28:29], v[28:29], 1, s[24:25]
	global_load_dwordx4 v[20:23], v[18:19], off offset:16
	global_load_dwordx4 v[24:27], v[18:19], off
	s_nop 0
	global_load_dwordx4 v[28:31], v[28:29], off nt
	s_waitcnt vmcnt(0)
	v_lshlrev_b32_e32 v34, 16, v28
	v_and_b32_e32 v35, 0xffff0000, v28
	v_pk_fma_f32 v[14:15], v[14:15], v[34:35], v[24:25]
	v_lshlrev_b32_e32 v24, 16, v29
	v_and_b32_e32 v25, 0xffff0000, v29
	v_pk_fma_f32 v[16:17], v[16:17], v[24:25], v[26:27]
	v_lshlrev_b32_e32 v24, 16, v30
	v_and_b32_e32 v25, 0xffff0000, v30
	v_pk_fma_f32 v[10:11], v[10:11], v[24:25], v[20:21]
	v_lshlrev_b32_e32 v20, 16, v31
	v_and_b32_e32 v21, 0xffff0000, v31
	v_pk_fma_f32 v[12:13], v[12:13], v[20:21], v[22:23]
	v_lshl_add_u64 v[20:21], v[32:33], 0, v[122:123]
	global_store_dwordx4 v[18:19], v[14:17], off
	global_store_dwordx4 v[18:19], v[10:13], off offset:16
	v_lshl_add_u64 v[20:21], v[20:21], 1, s[24:25]
	global_load_dwordx4 v[10:13], v[18:19], off offset:528
	global_load_dwordx4 v[14:17], v[18:19], off offset:512
	s_nop 0
	global_load_dwordx4 v[20:23], v[20:21], off nt
	s_waitcnt vmcnt(0)
	v_lshlrev_b32_e32 v24, 16, v20
	v_and_b32_e32 v25, 0xffff0000, v20
	v_pk_fma_f32 v[6:7], v[6:7], v[24:25], v[14:15]
	v_lshlrev_b32_e32 v14, 16, v21
	v_and_b32_e32 v15, 0xffff0000, v21
	v_pk_fma_f32 v[8:9], v[8:9], v[14:15], v[16:17]
	v_lshlrev_b32_e32 v14, 16, v22
	v_and_b32_e32 v15, 0xffff0000, v22
	v_pk_fma_f32 v[2:3], v[2:3], v[14:15], v[10:11]
	v_lshlrev_b32_e32 v10, 16, v23
	v_and_b32_e32 v11, 0xffff0000, v23
	v_pk_fma_f32 v[4:5], v[4:5], v[10:11], v[12:13]
	global_store_dwordx4 v[18:19], v[6:9], off offset:512
	global_store_dwordx4 v[18:19], v[2:5], off offset:528
	s_cbranch_vccnz .LBB0_924
	s_andn2_b64 vcc, exec, s[46:47]
	s_cbranch_vccnz .LBB0_923
	s_barrier
	s_branch .LBB0_923
